# P2 two queues: 160 workgroups (blockIdx>>3 < 20) pull sample attention first, 96 pull prompt attention + conv first
# baseline (speedup 1.0000x reference)
.LBB0_436:
	v_readlane_b32 s100, v248, 42
	s_mov_b32 s101, 0
	s_lshr_b32 s100, s100, 3
	s_and_b32 s100, s100, 31
	s_cmpk_lt_u32 s100, 20
	s_cselect_b32 s100, 1, 0
	s_load_dwordx4 s[28:31], s[52:53], 0x80
	s_waitcnt lgkmcnt(0)
	s_cmp_lt_i32 s30, 3
	s_cselect_b64 s[0:1], -1, 0
	s_and_b64 s[0:1], s[0:1], s[6:7]
	s_andn2_b64 vcc, exec, s[0:1]
	s_cbranch_vccnz .LBB0_610
	s_load_dwordx16 s[12:27], s[52:53], 0x0
	v_writelane_b32 v248, s0, 48
	v_mbcnt_lo_u32_b32 v3, -1, 0
	s_mov_b32 s11, 0x27000
	v_writelane_b32 v248, s1, 49
	s_waitcnt lgkmcnt(0)
	s_mov_b64 s[6:7], s[18:19]
	s_and_b32 s9, s7, 0xffff
	v_writelane_b32 v248, s33, 46
	s_add_u32 s0, s28, 0x2900000
	v_writelane_b32 v248, s0, 47
	s_addc_u32 s0, s29, 0
	v_writelane_b32 v248, s0, 44
	s_add_i32 s2, 0, 0x23200
	s_brev_b32 s10, -2
	s_mov_b32 s8, s18
	s_mov_b64 s[0:1], -1
	s_mov_b32 s21, 0
	v_mov_b32_e32 v2, 0
	v_writelane_b32 v248, s2, 38
	v_mov_b32_e32 v1, s2
	s_add_i32 s51, 0, 0x20000
	s_movk_i32 s33, 0x1000
	s_movk_i32 s50, 0x2000
	s_add_i32 s2, 0, 0x20800
	s_movk_i32 s19, 0x3000
	s_add_i32 s46, 0, 0x10000
	s_movk_i32 s6, 0x4000
	s_movk_i32 s17, 0x6000
	s_mov_b32 s31, 0x41000000
	s_movk_i32 s22, 0x5000
	s_movk_i32 s30, 0x7000
	v_mov_b32_e32 v204, 0x358637bd
	s_mov_b32 s18, 0xf800000
	v_mov_b32_e32 v205, 0x260
	v_mov_b32_e32 v196, 0xe0ad78ec
	v_mbcnt_hi_u32_b32 v206, -1, v3
	v_mov_b32_e32 v207, 3
	v_mov_b32_e32 v208, 2
	v_mov_b32_e32 v209, 1
	s_mov_b64 s[26:27], 0x100
	s_mov_b64 s[28:29], 0x1800
	s_mov_b64 s[34:35], 0x1900
	v_writelane_b32 v248, s2, 50
	s_branch .LBB0_440
